# phase 13 conv+transpose rewritten: next tile's conv weights requested before its row prefetch so no wait drains the prefetch
# baseline (speedup 1.0000x reference)
.LBB0_256:
	v_readlane_b32 s2, v249, 14
	v_readlane_b32 s3, v249, 15
	v_readlane_b32 s4, v251, 10
	v_readlane_b32 s5, v251, 11
	v_readlane_b32 s6, v251, 12
	v_readlane_b32 s7, v251, 13
	v_readlane_b32 s8, v255, 6
	v_readlane_b32 s9, v249, 18
	v_lshrrev_b32_e32 v114, 4, v163
	v_and_b32_e32 v115, 15, v163
	v_mul_u32_u24_e32 v104, 0x1800, v114
	v_lshl_add_u32 v104, v115, 4, v104
	v_add_u32_e32 v116, 0, v114
	v_lshrrev_b32_e32 v117, 3, v116
	v_add_lshl_u32 v117, v117, v115, 2
	v_and_b32_e32 v117, 63, v117
	v_lshl_add_u32 v117, v116, 6, v117
	v_lshlrev_b32_e32 v48, 2, v117
	v_add_u32_e32 v116, 32, v114
	v_lshrrev_b32_e32 v117, 3, v116
	v_add_lshl_u32 v117, v117, v115, 2
	v_and_b32_e32 v117, 63, v117
	v_lshl_add_u32 v117, v116, 6, v117
	v_lshlrev_b32_e32 v49, 2, v117
	v_add_u32_e32 v116, 64, v114
	v_lshrrev_b32_e32 v117, 3, v116
	v_add_lshl_u32 v117, v117, v115, 2
	v_and_b32_e32 v117, 63, v117
	v_lshl_add_u32 v117, v116, 6, v117
	v_lshlrev_b32_e32 v50, 2, v117
	v_add_u32_e32 v116, 96, v114
	v_lshrrev_b32_e32 v117, 3, v116
	v_add_lshl_u32 v117, v117, v115, 2
	v_and_b32_e32 v117, 63, v117
	v_lshl_add_u32 v117, v116, 6, v117
	v_lshlrev_b32_e32 v51, 2, v117
	v_add_u32_e32 v118, 0, v114
	v_lshl_add_u32 v119, v115, 2, v118
	v_and_b32_e32 v119, 63, v119
	v_lshl_add_u32 v119, v115, 9, v119
	v_lshlrev_b32_e32 v53, 2, v119
	v_lshl_add_u32 v119, v115, 2, v118
	v_add_u32_e32 v119, -4, v119
	v_and_b32_e32 v119, 63, v119
	v_lshlrev_b32_e32 v120, 9, v115
	v_add_u32_e32 v120, -64, v120
	v_add_lshl_u32 v52, v120, v119, 2
	v_lshl_add_u32 v119, v115, 2, v118
	v_add_u32_e32 v119, 4, v119
	v_and_b32_e32 v119, 63, v119
	v_lshlrev_b32_e32 v120, 9, v115
	v_add_u32_e32 v120, 0x200, v120
	v_add_lshl_u32 v54, v120, v119, 2
	v_lshlrev_b32_e32 v106, 15, v118
	v_lshl_add_u32 v106, v115, 4, v106
	v_add_u32_e32 v107, 0x4000, v106
	v_lshlrev_b32_e32 v110, 3, v118
	v_add_u32_e32 v118, 32, v114
	v_lshl_add_u32 v119, v115, 2, v118
	v_and_b32_e32 v119, 63, v119
	v_lshl_add_u32 v119, v115, 9, v119
	v_lshlrev_b32_e32 v56, 2, v119
	v_lshl_add_u32 v119, v115, 2, v118
	v_add_u32_e32 v119, -4, v119
	v_and_b32_e32 v119, 63, v119
	v_lshlrev_b32_e32 v120, 9, v115
	v_add_u32_e32 v120, -64, v120
	v_add_lshl_u32 v55, v120, v119, 2
	v_lshl_add_u32 v119, v115, 2, v118
	v_add_u32_e32 v119, 4, v119
	v_and_b32_e32 v119, 63, v119
	v_lshlrev_b32_e32 v120, 9, v115
	v_add_u32_e32 v120, 0x200, v120
	v_add_lshl_u32 v57, v120, v119, 2
	v_lshlrev_b32_e32 v108, 15, v118
	v_lshl_add_u32 v108, v115, 4, v108
	v_add_u32_e32 v109, 0x4000, v108
	v_lshlrev_b32_e32 v111, 3, v118
	v_and_b32_e32 v119, 7, v115
	v_cmp_ne_u32_e64 s[20:21], 0, v119
	v_cmp_ne_u32_e64 s[22:23], 7, v119
	s_nop 1
	v_cndmask_b32_e64 v52, v53, v52, s[20:21]
	v_cndmask_b32_e64 v54, v53, v54, s[22:23]
	s_nop 1
	v_cndmask_b32_e64 v55, v56, v55, s[20:21]
	v_cndmask_b32_e64 v57, v56, v57, s[22:23]
	s_mul_hi_u32 s12, s8, 0xAAAAAAAB
	s_lshr_b32 s12, s12, 4
	s_mul_i32 s24, s12, 24
	s_sub_u32 s10, s8, s24
	s_mul_hi_u32 s14, s9, 0xAAAAAAAB
	s_lshr_b32 s14, s14, 4
	s_mul_i32 s24, s14, 24
	s_sub_u32 s13, s9, s24
	s_mov_b32 s15, 0
	s_cmp_lt_u32 s8, 0x1800
	s_cbranch_scc0 .LcT_none
	s_mul_i32 s24, s12, 0xC0000
	s_lshl_b32 s25, s10, 8
	s_add_u32 s24, s24, s25
	s_add_u32 s24, s24, 0x8000000
	s_add_u32 s16, s2, s24
	s_addc_u32 s17, s3, 0
	s_lshl_b32 s25, s10, 9
	v_add_u32_e32 v112, s25, v110
	v_add_u32_e32 v113, s25, v111
	global_load_dwordx2 v[22:23], v112, s[6:7]
	global_load_dwordx2 v[16:17], v112, s[4:5]
	v_add_u32_e32 v112, 0x3000, v112
	global_load_dwordx2 v[18:19], v112, s[4:5]
	v_add_u32_e32 v112, 0x3000, v112
	global_load_dwordx2 v[20:21], v112, s[4:5]
	global_load_dwordx2 v[30:31], v113, s[6:7]
	global_load_dwordx2 v[24:25], v113, s[4:5]
	v_add_u32_e32 v113, 0x3000, v113
	global_load_dwordx2 v[26:27], v113, s[4:5]
	v_add_u32_e32 v113, 0x3000, v113
	global_load_dwordx2 v[28:29], v113, s[4:5]
	v_mov_b32_e32 v105, v104
	global_load_dwordx4 v[0:3], v105, s[16:17] nt
	v_add_u32_e32 v105, 0x30000, v105
	global_load_dwordx4 v[4:7], v105, s[16:17] nt
	v_add_u32_e32 v105, 0x30000, v105
	global_load_dwordx4 v[8:11], v105, s[16:17] nt
	v_add_u32_e32 v105, 0x30000, v105
	global_load_dwordx4 v[12:15], v105, s[16:17] nt
.LcT_none:
	s_waitcnt vmcnt(0) lgkmcnt(0)
	s_barrier
	s_cmp_lt_u32 s8, 0x1800
	s_cbranch_scc0 .LcT_done
.LcT_tile:
	s_lshr_b32 s24, s10, 3
	s_lshl_b32 s24, s24, 2
	s_lshr_b32 s25, s12, 6
	s_add_u32 s24, s24, s25
	s_lshl_b32 s24, s24, 24
	s_and_b32 s25, s10, 7
	s_lshl_b32 s25, s25, 21
	s_add_u32 s24, s24, s25
	s_and_b32 s25, s12, 63
	s_lshl_b32 s25, s25, 8
	s_add_u32 s24, s24, s25
	s_add_u32 s24, s24, 0x14000000
	s_add_u32 s18, s2, s24
	s_addc_u32 s19, s3, 0
	v_mov_b32_e32 v32, v16
	v_mov_b32_e32 v33, v17
	v_mov_b32_e32 v34, v18
	v_mov_b32_e32 v35, v19
	v_mov_b32_e32 v36, v20
	v_mov_b32_e32 v37, v21
	v_mov_b32_e32 v38, v22
	v_mov_b32_e32 v39, v23
	v_mov_b32_e32 v40, v24
	v_mov_b32_e32 v41, v25
	v_mov_b32_e32 v42, v26
	v_mov_b32_e32 v43, v27
	v_mov_b32_e32 v44, v28
	v_mov_b32_e32 v45, v29
	v_mov_b32_e32 v46, v30
	v_mov_b32_e32 v47, v31
	v_add_u32_e32 v114, s15, v48
	ds_write_b128 v114, v[0:3]
	v_add_u32_e32 v114, s15, v49
	ds_write_b128 v114, v[4:7]
	v_add_u32_e32 v114, s15, v50
	ds_write_b128 v114, v[8:11]
	v_add_u32_e32 v114, s15, v51
	ds_write_b128 v114, v[12:15]
	s_add_u32 s8, s8, s9
	s_add_u32 s10, s10, s13
	s_add_u32 s12, s12, s14
	s_cmp_ge_u32 s10, 24
	s_cbranch_scc0 .LcT_nowrap
	s_sub_u32 s10, s10, 24
	s_add_u32 s12, s12, 1
.LcT_nowrap:
	s_cmp_lt_u32 s8, 0x1800
	s_cselect_b32 s0, 1, 0
	s_cbranch_scc0 .LcT_nonext
	s_mul_i32 s24, s12, 0xC0000
	s_lshl_b32 s25, s10, 8
	s_add_u32 s24, s24, s25
	s_add_u32 s24, s24, 0x8000000
	s_add_u32 s16, s2, s24
	s_addc_u32 s17, s3, 0
	s_lshl_b32 s25, s10, 9
	v_add_u32_e32 v112, s25, v110
	v_add_u32_e32 v113, s25, v111
	global_load_dwordx2 v[22:23], v112, s[6:7]
	global_load_dwordx2 v[16:17], v112, s[4:5]
	v_add_u32_e32 v112, 0x3000, v112
	global_load_dwordx2 v[18:19], v112, s[4:5]
	v_add_u32_e32 v112, 0x3000, v112
	global_load_dwordx2 v[20:21], v112, s[4:5]
	global_load_dwordx2 v[30:31], v113, s[6:7]
	global_load_dwordx2 v[24:25], v113, s[4:5]
	v_add_u32_e32 v113, 0x3000, v113
	global_load_dwordx2 v[26:27], v113, s[4:5]
	v_add_u32_e32 v113, 0x3000, v113
	global_load_dwordx2 v[28:29], v113, s[4:5]
	v_mov_b32_e32 v105, v104
	global_load_dwordx4 v[0:3], v105, s[16:17] nt
	v_add_u32_e32 v105, 0x30000, v105
	global_load_dwordx4 v[4:7], v105, s[16:17] nt
	v_add_u32_e32 v105, 0x30000, v105
	global_load_dwordx4 v[8:11], v105, s[16:17] nt
	v_add_u32_e32 v105, 0x30000, v105
	global_load_dwordx4 v[12:15], v105, s[16:17] nt
.LcT_nonext:
	s_waitcnt lgkmcnt(0)
	s_barrier
	v_add_u32_e32 v114, s15, v53
	v_add_u32_e32 v115, s15, v52
	v_add_u32_e32 v116, s15, v54
	ds_read_b32 v123, v115
	ds_read2st64_b32 v[124:125], v114 offset0:0 offset1:1
	ds_read2st64_b32 v[126:127], v114 offset0:2 offset1:3
	ds_read2st64_b32 v[128:129], v114 offset0:4 offset1:5
	ds_read2st64_b32 v[130:131], v114 offset0:6 offset1:7
	ds_read_b32 v132, v116
	s_waitcnt lgkmcnt(0)
	v_cndmask_b32_e64 v123, 0, v123, s[20:21]
	v_cndmask_b32_e64 v132, 0, v132, s[22:23]
	v_lshlrev_b32_e32 v60, 16, v123
	v_and_b32_e32 v61, 0xffff0000, v123
	v_lshlrev_b32_e32 v62, 16, v124
	v_and_b32_e32 v63, 0xffff0000, v124
	v_lshlrev_b32_e32 v64, 16, v125
	v_and_b32_e32 v65, 0xffff0000, v125
	v_lshlrev_b32_e32 v66, 16, v126
	v_and_b32_e32 v67, 0xffff0000, v126
	v_lshlrev_b32_e32 v68, 16, v127
	v_and_b32_e32 v69, 0xffff0000, v127
	v_lshlrev_b32_e32 v70, 16, v128
	v_and_b32_e32 v71, 0xffff0000, v128
	v_lshlrev_b32_e32 v72, 16, v129
	v_and_b32_e32 v73, 0xffff0000, v129
	v_lshlrev_b32_e32 v74, 16, v130
	v_and_b32_e32 v75, 0xffff0000, v130
	v_lshlrev_b32_e32 v76, 16, v131
	v_and_b32_e32 v77, 0xffff0000, v131
	v_lshlrev_b32_e32 v78, 16, v132
	v_and_b32_e32 v79, 0xffff0000, v132
	v_pk_fma_f32 v[80:81], v[32:33], v[60:61], v[38:39]
	v_pk_fma_f32 v[82:83], v[32:33], v[62:63], v[38:39]
	v_pk_fma_f32 v[84:85], v[32:33], v[64:65], v[38:39]
	v_pk_fma_f32 v[86:87], v[32:33], v[66:67], v[38:39]
	v_pk_fma_f32 v[88:89], v[32:33], v[68:69], v[38:39]
	v_pk_fma_f32 v[90:91], v[32:33], v[70:71], v[38:39]
	v_pk_fma_f32 v[92:93], v[32:33], v[72:73], v[38:39]
	v_pk_fma_f32 v[94:95], v[32:33], v[74:75], v[38:39]
	v_pk_fma_f32 v[80:81], v[34:35], v[62:63], v[80:81]
	v_pk_fma_f32 v[82:83], v[34:35], v[64:65], v[82:83]
	v_pk_fma_f32 v[84:85], v[34:35], v[66:67], v[84:85]
	v_pk_fma_f32 v[86:87], v[34:35], v[68:69], v[86:87]
	v_pk_fma_f32 v[88:89], v[34:35], v[70:71], v[88:89]
	v_pk_fma_f32 v[90:91], v[34:35], v[72:73], v[90:91]
	v_pk_fma_f32 v[92:93], v[34:35], v[74:75], v[92:93]
	v_pk_fma_f32 v[94:95], v[34:35], v[76:77], v[94:95]
	v_pk_fma_f32 v[80:81], v[36:37], v[64:65], v[80:81]
	v_pk_fma_f32 v[82:83], v[36:37], v[66:67], v[82:83]
	v_pk_fma_f32 v[84:85], v[36:37], v[68:69], v[84:85]
	v_pk_fma_f32 v[86:87], v[36:37], v[70:71], v[86:87]
	v_pk_fma_f32 v[88:89], v[36:37], v[72:73], v[88:89]
	v_pk_fma_f32 v[90:91], v[36:37], v[74:75], v[90:91]
	v_pk_fma_f32 v[92:93], v[36:37], v[76:77], v[92:93]
	v_pk_fma_f32 v[94:95], v[36:37], v[78:79], v[94:95]
	v_cvt_pk_bf16_f32 v96, v80, v82
	v_cvt_pk_bf16_f32 v97, v84, v86
	v_cvt_pk_bf16_f32 v98, v88, v90
	v_cvt_pk_bf16_f32 v99, v92, v94
	v_cvt_pk_bf16_f32 v100, v81, v83
	v_cvt_pk_bf16_f32 v101, v85, v87
	v_cvt_pk_bf16_f32 v102, v89, v91
	v_cvt_pk_bf16_f32 v103, v93, v95
	global_store_dwordx4 v106, v[96:99], s[18:19]
	global_store_dwordx4 v107, v[100:103], s[18:19]
	v_add_u32_e32 v114, s15, v56
	v_add_u32_e32 v115, s15, v55
	v_add_u32_e32 v116, s15, v57
	ds_read_b32 v123, v115
	ds_read2st64_b32 v[124:125], v114 offset0:0 offset1:1
	ds_read2st64_b32 v[126:127], v114 offset0:2 offset1:3
	ds_read2st64_b32 v[128:129], v114 offset0:4 offset1:5
	ds_read2st64_b32 v[130:131], v114 offset0:6 offset1:7
	ds_read_b32 v132, v116
	s_waitcnt lgkmcnt(0)
	v_cndmask_b32_e64 v123, 0, v123, s[20:21]
	v_cndmask_b32_e64 v132, 0, v132, s[22:23]
	v_lshlrev_b32_e32 v60, 16, v123
	v_and_b32_e32 v61, 0xffff0000, v123
	v_lshlrev_b32_e32 v62, 16, v124
	v_and_b32_e32 v63, 0xffff0000, v124
	v_lshlrev_b32_e32 v64, 16, v125
	v_and_b32_e32 v65, 0xffff0000, v125
	v_lshlrev_b32_e32 v66, 16, v126
	v_and_b32_e32 v67, 0xffff0000, v126
	v_lshlrev_b32_e32 v68, 16, v127
	v_and_b32_e32 v69, 0xffff0000, v127
	v_lshlrev_b32_e32 v70, 16, v128
	v_and_b32_e32 v71, 0xffff0000, v128
	v_lshlrev_b32_e32 v72, 16, v129
	v_and_b32_e32 v73, 0xffff0000, v129
	v_lshlrev_b32_e32 v74, 16, v130
	v_and_b32_e32 v75, 0xffff0000, v130
	v_lshlrev_b32_e32 v76, 16, v131
	v_and_b32_e32 v77, 0xffff0000, v131
	v_lshlrev_b32_e32 v78, 16, v132
	v_and_b32_e32 v79, 0xffff0000, v132
	v_pk_fma_f32 v[80:81], v[40:41], v[60:61], v[46:47]
	v_pk_fma_f32 v[82:83], v[40:41], v[62:63], v[46:47]
	v_pk_fma_f32 v[84:85], v[40:41], v[64:65], v[46:47]
	v_pk_fma_f32 v[86:87], v[40:41], v[66:67], v[46:47]
	v_pk_fma_f32 v[88:89], v[40:41], v[68:69], v[46:47]
	v_pk_fma_f32 v[90:91], v[40:41], v[70:71], v[46:47]
	v_pk_fma_f32 v[92:93], v[40:41], v[72:73], v[46:47]
	v_pk_fma_f32 v[94:95], v[40:41], v[74:75], v[46:47]
	v_pk_fma_f32 v[80:81], v[42:43], v[62:63], v[80:81]
	v_pk_fma_f32 v[82:83], v[42:43], v[64:65], v[82:83]
	v_pk_fma_f32 v[84:85], v[42:43], v[66:67], v[84:85]
	v_pk_fma_f32 v[86:87], v[42:43], v[68:69], v[86:87]
	v_pk_fma_f32 v[88:89], v[42:43], v[70:71], v[88:89]
	v_pk_fma_f32 v[90:91], v[42:43], v[72:73], v[90:91]
	v_pk_fma_f32 v[92:93], v[42:43], v[74:75], v[92:93]
	v_pk_fma_f32 v[94:95], v[42:43], v[76:77], v[94:95]
	v_pk_fma_f32 v[80:81], v[44:45], v[64:65], v[80:81]
	v_pk_fma_f32 v[82:83], v[44:45], v[66:67], v[82:83]
	v_pk_fma_f32 v[84:85], v[44:45], v[68:69], v[84:85]
	v_pk_fma_f32 v[86:87], v[44:45], v[70:71], v[86:87]
	v_pk_fma_f32 v[88:89], v[44:45], v[72:73], v[88:89]
	v_pk_fma_f32 v[90:91], v[44:45], v[74:75], v[90:91]
	v_pk_fma_f32 v[92:93], v[44:45], v[76:77], v[92:93]
	v_pk_fma_f32 v[94:95], v[44:45], v[78:79], v[94:95]
	v_cvt_pk_bf16_f32 v96, v80, v82
	v_cvt_pk_bf16_f32 v97, v84, v86
	v_cvt_pk_bf16_f32 v98, v88, v90
	v_cvt_pk_bf16_f32 v99, v92, v94
	v_cvt_pk_bf16_f32 v100, v81, v83
	v_cvt_pk_bf16_f32 v101, v85, v87
	v_cvt_pk_bf16_f32 v102, v89, v91
	v_cvt_pk_bf16_f32 v103, v93, v95
	global_store_dwordx4 v108, v[96:99], s[18:19]
	global_store_dwordx4 v109, v[100:103], s[18:19]
	s_xor_b32 s15, s15, 0x8000
	s_cmp_eq_u32 s0, 1
	s_cbranch_scc0 .LcT_done
	s_waitcnt vmcnt(4)
	s_branch .LcT_tile
.LcT_done:
.LBB0_271:
	s_barrier
